# v12 with the GEMM K-loop head aligned to 64 bytes (placement experiment)
# speedup vs baseline: 1.0085x; 1.0085x over previous
.Lkt_nt:
	s_add_i32 s100, s101, -2
	s_and_b64 s[2:3], s[42:43], exec
	v_mov_b32_e32 v0, 0
	s_cselect_b32 s2, s22, s44
	s_add_i32 s3, s45, 0x80
	s_add_i32 s42, s44, 0x100
	s_mov_b32 s43, 0
	v_mov_b32_e32 v1, v0
	v_mov_b32_e32 v2, v0
	v_mov_b32_e32 v3, v0
	v_mov_b32_e32 v4, v0
	v_mov_b32_e32 v5, v0
	v_mov_b32_e32 v6, v0
	v_mov_b32_e32 v7, v0
	v_mov_b32_e32 v16, v0
	v_mov_b32_e32 v17, v0
	v_mov_b32_e32 v18, v0
	v_mov_b32_e32 v19, v0
	v_mov_b32_e32 v20, v0
	v_mov_b32_e32 v21, v0
	v_mov_b32_e32 v22, v0
	v_mov_b32_e32 v23, v0
	v_mov_b32_e32 v32, v0
	v_mov_b32_e32 v33, v0
	v_mov_b32_e32 v34, v0
	v_mov_b32_e32 v35, v0
	v_mov_b32_e32 v36, v0
	v_mov_b32_e32 v37, v0
	v_mov_b32_e32 v38, v0
	v_mov_b32_e32 v39, v0
	v_mov_b32_e32 v48, v0
	v_mov_b32_e32 v49, v0
	v_mov_b32_e32 v50, v0
	v_mov_b32_e32 v51, v0
	v_mov_b32_e32 v52, v0
	v_mov_b32_e32 v53, v0
	v_mov_b32_e32 v54, v0
	v_mov_b32_e32 v55, v0
	v_mov_b32_e32 v8, v0
	v_mov_b32_e32 v9, v0
	v_mov_b32_e32 v10, v0
	v_mov_b32_e32 v11, v0
	v_mov_b32_e32 v12, v0
	v_mov_b32_e32 v13, v0
	v_mov_b32_e32 v14, v0
	v_mov_b32_e32 v15, v0
	v_mov_b32_e32 v24, v0
	v_mov_b32_e32 v25, v0
	v_mov_b32_e32 v26, v0
	v_mov_b32_e32 v27, v0
	v_mov_b32_e32 v28, v0
	v_mov_b32_e32 v29, v0
	v_mov_b32_e32 v30, v0
	v_mov_b32_e32 v31, v0
	v_mov_b32_e32 v40, v0
	v_mov_b32_e32 v41, v0
	v_mov_b32_e32 v42, v0
	v_mov_b32_e32 v43, v0
	v_mov_b32_e32 v44, v0
	v_mov_b32_e32 v45, v0
	v_mov_b32_e32 v46, v0
	v_mov_b32_e32 v47, v0
	v_mov_b32_e32 v56, v0
	v_mov_b32_e32 v57, v0
	v_mov_b32_e32 v58, v0
	v_mov_b32_e32 v59, v0
	v_mov_b32_e32 v60, v0
	v_mov_b32_e32 v61, v0
	v_mov_b32_e32 v62, v0
	v_mov_b32_e32 v63, v0
	v_mov_b32_e32 v64, v0
	v_mov_b32_e32 v65, v0
	v_mov_b32_e32 v66, v0
	v_mov_b32_e32 v67, v0
	v_mov_b32_e32 v68, v0
	v_mov_b32_e32 v69, v0
	v_mov_b32_e32 v70, v0
	v_mov_b32_e32 v71, v0
	v_mov_b32_e32 v80, v0
	v_mov_b32_e32 v81, v0
	v_mov_b32_e32 v82, v0
	v_mov_b32_e32 v83, v0
	v_mov_b32_e32 v84, v0
	v_mov_b32_e32 v85, v0
	v_mov_b32_e32 v86, v0
	v_mov_b32_e32 v87, v0
	v_mov_b32_e32 v96, v0
	v_mov_b32_e32 v97, v0
	v_mov_b32_e32 v98, v0
	v_mov_b32_e32 v99, v0
	v_mov_b32_e32 v100, v0
	v_mov_b32_e32 v101, v0
	v_mov_b32_e32 v102, v0
	v_mov_b32_e32 v103, v0
	v_mov_b32_e32 v112, v0
	v_mov_b32_e32 v113, v0
	v_mov_b32_e32 v114, v0
	v_mov_b32_e32 v115, v0
	v_mov_b32_e32 v116, v0
	v_mov_b32_e32 v117, v0
	v_mov_b32_e32 v118, v0
	v_mov_b32_e32 v119, v0
	v_mov_b32_e32 v72, v0
	v_mov_b32_e32 v73, v0
	v_mov_b32_e32 v74, v0
	v_mov_b32_e32 v75, v0
	v_mov_b32_e32 v76, v0
	v_mov_b32_e32 v77, v0
	v_mov_b32_e32 v78, v0
	v_mov_b32_e32 v79, v0
	v_mov_b32_e32 v88, v0
	v_mov_b32_e32 v89, v0
	v_mov_b32_e32 v90, v0
	v_mov_b32_e32 v91, v0
	v_mov_b32_e32 v92, v0
	v_mov_b32_e32 v93, v0
	v_mov_b32_e32 v94, v0
	v_mov_b32_e32 v95, v0
	v_mov_b32_e32 v104, v0
	v_mov_b32_e32 v105, v0
	v_mov_b32_e32 v106, v0
	v_mov_b32_e32 v107, v0
	v_mov_b32_e32 v108, v0
	v_mov_b32_e32 v109, v0
	v_mov_b32_e32 v110, v0
	v_mov_b32_e32 v111, v0
	v_mov_b32_e32 v120, v0
	v_mov_b32_e32 v121, v0
	v_mov_b32_e32 v122, v0
	v_mov_b32_e32 v123, v0
	v_mov_b32_e32 v124, v0
	v_mov_b32_e32 v125, v0
	v_mov_b32_e32 v126, v0
	v_mov_b32_e32 v127, v0
	.p2alignl 6, 3212836864
